# work-queue dequeue prefetch in P5: next ticket atomic issued right after publishing the current item, on top of v12
# baseline (speedup 1.0000x reference)
; #define LAS __attribute__((address_space(3)))
; #define PH_BEGIN const int tid = otid(); const int G = gridDim.x; const int bid = osi((int)blockIdx.x); unsigned char* ws = osp(P.ws); float* out = osp(P.out); unsigned char* U = ws + WS_U; (void)tid; (void)G; (void)bid; (void)out; (void)U;
; __global__ void __launch_bounds__(512, 2) mega(Params P) {
;     ...
;             LAS int* sitem = (LAS int*)(lds + LDS_MISC);
;     ...
;             for (int rep = 0; rep < REP_P5; ++rep)
;             for (;;) {
;                 PH_BEGIN
;                 __syncthreads();
;                 if (tid == 0) *sitem = (int)atomicAdd(WSP(unsigned, WS_CTL) + 3600 + l + 2 * rep, 1u);
;                 __syncthreads();
;                 const int it = *sitem;
;                 if (it >= 1280) break;
.LBB0_886:
	s_or_b64 exec, exec, s[0:1]
	s_lshl_b32 s0, s96, 3
	s_lshl_b32 s92, s96, 8
	v_readlane_b32 s72, v253, 0
	s_lshl_b32 s54, s96, 10
	s_lshl_b32 s36, s96, 14
	s_lshl_b32 s31, s96, 4
	v_writelane_b32 v254, s0, 38
	s_lshl_b64 s[0:1], s[92:93], 2
	v_readlane_b32 s86, v253, 14
	v_readlane_b32 s87, v253, 15
	s_add_u32 s37, s86, s0
	s_mov_b32 s0, s96
	s_addc_u32 s38, s87, s1
	v_writelane_b32 v254, s0, 56
	s_mov_b32 s2, s96
	s_mov_b32 s3, s93
	v_writelane_b32 v254, s1, 57
	s_lshl_b64 s[34:35], s[2:3], 2
	v_writelane_b32 v254, s31, 46
	s_waitcnt lgkmcnt(0)
	s_barrier
	v_readlane_b32 s73, v253, 1
	v_readlane_b32 s74, v253, 2
	v_readlane_b32 s75, v253, 3
	v_readlane_b32 s76, v253, 4
	v_readlane_b32 s77, v253, 5
	v_readlane_b32 s78, v253, 6
	v_readlane_b32 s79, v253, 7
	v_readlane_b32 s80, v253, 8
	v_readlane_b32 s81, v253, 9
	v_readlane_b32 s82, v253, 10
	v_readlane_b32 s83, v253, 11
	v_readlane_b32 s84, v253, 12
	v_readlane_b32 s85, v253, 13
	v_mbcnt_lo_u32_b32 v251, -1, 0
	v_mbcnt_hi_u32_b32 v251, -1, v251
	v_lshl_add_u32 v251, s21, 6, v251
	v_cmp_eq_u32_e32 vcc, 0, v251
	v_readlane_b32 s6, v254, 25
	v_readlane_b32 s7, v254, 26
	s_and_saveexec_b64 s[0:1], vcc
	s_cbranch_execz .Ldq_prime_skip
	s_add_u32 s6, s6, s34
	s_addc_u32 s7, s7, s35
	v_mov_b32_e32 v251, 1
	v_mov_b32_e32 v249, 0x3000
	global_atomic_add v250, v249, v251, s[6:7] offset:2112 sc0
.Ldq_prime_skip:
	s_or_b64 exec, exec, s[0:1]
	s_branch .LBB0_889

; #define PH_BEGIN const int tid = otid(); const int G = gridDim.x; const int bid = osi((int)blockIdx.x); unsigned char* ws = osp(P.ws); float* out = osp(P.out); unsigned char* U = ws + WS_U; (void)tid; (void)G; (void)bid; (void)out; (void)U;
; __global__ void __launch_bounds__(512, 2) mega(Params P) {
;     ...
;                 PH_BEGIN
;                 __syncthreads();
;                 if (tid == 0) *sitem = (int)atomicAdd(WSP(unsigned, WS_CTL) + 3600 + l + 2 * rep, 1u);
;                 __syncthreads();
;                 const int it = *sitem;
;                 if (it >= 1280) break;
.LBB0_889:
	s_mov_b32 s0, s21
	v_mbcnt_lo_u32_b32 v0, -1, 0
	v_mbcnt_hi_u32_b32 v0, -1, v0
	s_nop 0
	v_lshl_add_u32 v148, s0, 6, v0
	s_mov_b32 s0, s97
	v_cmp_eq_u32_e32 vcc, 0, v148
	v_readlane_b32 s0, v254, 19
	v_readlane_b32 s4, v254, 23
	v_readlane_b32 s5, v254, 24
	v_readlane_b32 s6, v254, 25
	v_readlane_b32 s7, v254, 26
	v_readlane_b32 s1, v254, 20
	s_mov_b64 s[52:53], s[6:7]
	s_mov_b64 s[16:17], s[4:5]
	v_readlane_b32 s2, v254, 21
	v_readlane_b32 s3, v254, 22
	s_barrier
	s_and_saveexec_b64 s[0:1], vcc
	s_cbranch_execz .LBB0_893
	s_add_u32 s6, s52, s34
	s_addc_u32 s7, s53, s35
	v_mov_b32_e32 v1, s89
	v_mov_b32_e32 v251, 1
	v_mov_b32_e32 v249, 0x3000
	s_waitcnt vmcnt(0)
	v_readfirstlane_b32 s2, v250
	s_nop 0
	v_mov_b32_e32 v0, s2
	ds_write_b32 v1, v0
	global_atomic_add v250, v249, v251, s[6:7] offset:2112 sc0
